# phase D preamble: gain-maximum loop (8 iterations of 4 loads + waits) fully unrolled into 32 loads issued together
# speedup vs baseline: 1.0024x; 1.0024x over previous
.LBB0_704:
	global_load_dwordx4 v[8:11], v177, s[2:3]
	global_load_dwordx4 v[12:15], v177, s[2:3] offset:16
	global_load_dwordx4 v[16:19], v177, s[2:3] offset:32
	global_load_dwordx4 v[20:23], v177, s[2:3] offset:48
	global_load_dwordx4 v[24:27], v177, s[2:3] offset:64
	global_load_dwordx4 v[28:31], v177, s[2:3] offset:80
	global_load_dwordx4 v[32:35], v177, s[2:3] offset:96
	global_load_dwordx4 v[36:39], v177, s[2:3] offset:112
	global_load_dwordx4 v[40:43], v177, s[2:3] offset:128
	global_load_dwordx4 v[44:47], v177, s[2:3] offset:144
	global_load_dwordx4 v[48:51], v177, s[2:3] offset:160
	global_load_dwordx4 v[52:55], v177, s[2:3] offset:176
	global_load_dwordx4 v[56:59], v177, s[2:3] offset:192
	global_load_dwordx4 v[60:63], v177, s[2:3] offset:208
	global_load_dwordx4 v[64:67], v177, s[2:3] offset:224
	global_load_dwordx4 v[68:71], v177, s[2:3] offset:240
	global_load_dwordx4 v[72:75], v177, s[4:5]
	global_load_dwordx4 v[76:79], v177, s[4:5] offset:16
	global_load_dwordx4 v[80:83], v177, s[4:5] offset:32
	global_load_dwordx4 v[84:87], v177, s[4:5] offset:48
	global_load_dwordx4 v[88:91], v177, s[4:5] offset:64
	global_load_dwordx4 v[92:95], v177, s[4:5] offset:80
	global_load_dwordx4 v[96:99], v177, s[4:5] offset:96
	global_load_dwordx4 v[100:103], v177, s[4:5] offset:112
	global_load_dwordx4 v[104:107], v177, s[4:5] offset:128
	global_load_dwordx4 v[108:111], v177, s[4:5] offset:144
	global_load_dwordx4 v[112:115], v177, s[4:5] offset:160
	global_load_dwordx4 v[116:119], v177, s[4:5] offset:176
	global_load_dwordx4 v[120:123], v177, s[4:5] offset:192
	global_load_dwordx4 v[124:127], v177, s[4:5] offset:208
	global_load_dwordx4 v[128:131], v177, s[4:5] offset:224
	global_load_dwordx4 v[132:135], v177, s[4:5] offset:240
	s_waitcnt vmcnt(16)
	v_max3_f32 v3, v3, |v8|, |v9|
	v_max3_f32 v3, v3, |v10|, |v11|
	v_max3_f32 v3, v3, |v12|, |v13|
	v_max3_f32 v3, v3, |v14|, |v15|
	v_max3_f32 v3, v3, |v16|, |v17|
	v_max3_f32 v3, v3, |v18|, |v19|
	v_max3_f32 v3, v3, |v20|, |v21|
	v_max3_f32 v3, v3, |v22|, |v23|
	v_max3_f32 v3, v3, |v24|, |v25|
	v_max3_f32 v3, v3, |v26|, |v27|
	v_max3_f32 v3, v3, |v28|, |v29|
	v_max3_f32 v3, v3, |v30|, |v31|
	v_max3_f32 v3, v3, |v32|, |v33|
	v_max3_f32 v3, v3, |v34|, |v35|
	v_max3_f32 v3, v3, |v36|, |v37|
	v_max3_f32 v3, v3, |v38|, |v39|
	v_max3_f32 v3, v3, |v40|, |v41|
	v_max3_f32 v3, v3, |v42|, |v43|
	v_max3_f32 v3, v3, |v44|, |v45|
	v_max3_f32 v3, v3, |v46|, |v47|
	v_max3_f32 v3, v3, |v48|, |v49|
	v_max3_f32 v3, v3, |v50|, |v51|
	v_max3_f32 v3, v3, |v52|, |v53|
	v_max3_f32 v3, v3, |v54|, |v55|
	v_max3_f32 v3, v3, |v56|, |v57|
	v_max3_f32 v3, v3, |v58|, |v59|
	v_max3_f32 v3, v3, |v60|, |v61|
	v_max3_f32 v3, v3, |v62|, |v63|
	v_max3_f32 v3, v3, |v64|, |v65|
	v_max3_f32 v3, v3, |v66|, |v67|
	v_max3_f32 v3, v3, |v68|, |v69|
	v_max3_f32 v3, v3, |v70|, |v71|
	s_waitcnt vmcnt(0)
	v_max3_f32 v2, v2, |v72|, |v73|
	v_max3_f32 v2, v2, |v74|, |v75|
	v_max3_f32 v2, v2, |v76|, |v77|
	v_max3_f32 v2, v2, |v78|, |v79|
	v_max3_f32 v2, v2, |v80|, |v81|
	v_max3_f32 v2, v2, |v82|, |v83|
	v_max3_f32 v2, v2, |v84|, |v85|
	v_max3_f32 v2, v2, |v86|, |v87|
	v_max3_f32 v2, v2, |v88|, |v89|
	v_max3_f32 v2, v2, |v90|, |v91|
	v_max3_f32 v2, v2, |v92|, |v93|
	v_max3_f32 v2, v2, |v94|, |v95|
	v_max3_f32 v2, v2, |v96|, |v97|
	v_max3_f32 v2, v2, |v98|, |v99|
	v_max3_f32 v2, v2, |v100|, |v101|
	v_max3_f32 v2, v2, |v102|, |v103|
	v_max3_f32 v2, v2, |v104|, |v105|
	v_max3_f32 v2, v2, |v106|, |v107|
	v_max3_f32 v2, v2, |v108|, |v109|
	v_max3_f32 v2, v2, |v110|, |v111|
	v_max3_f32 v2, v2, |v112|, |v113|
	v_max3_f32 v2, v2, |v114|, |v115|
	v_max3_f32 v2, v2, |v116|, |v117|
	v_max3_f32 v2, v2, |v118|, |v119|
	v_max3_f32 v2, v2, |v120|, |v121|
	v_max3_f32 v2, v2, |v122|, |v123|
	v_max3_f32 v2, v2, |v124|, |v125|
	v_max3_f32 v2, v2, |v126|, |v127|
	v_max3_f32 v2, v2, |v128|, |v129|
	v_max3_f32 v2, v2, |v130|, |v131|
	v_max3_f32 v2, v2, |v132|, |v133|
	v_max3_f32 v2, v2, |v134|, |v135|
	v_mov_b32_e32 v4, v179
	s_movk_i32 s0, 0x2200
	v_mov_b32_e32 v5, 0
	v_cmp_gt_i32_e32 vcc, s0, v4
	v_mov_b32_e32 v6, 0
	s_and_saveexec_b64 s[0:1], vcc
	s_cbranch_execz .LBB0_709
	v_readlane_b32 s2, v254, 41
	v_readlane_b32 s3, v254, 42
	s_mul_i32 s96, s2, 0x4400
	s_lshl_b64 s[2:3], s[96:97], 2
	v_readlane_b32 s4, v253, 34
	v_readlane_b32 s5, v253, 35
	s_add_u32 s2, s4, s2
	s_addc_u32 s3, s5, s3
	v_add_u32_e32 v7, 0xffffff00, v4
	v_lshlrev_b32_e32 v0, 1, v4
	v_mov_b32_e32 v5, 0
	s_mov_b64 s[4:5], 0
	v_mov_b32_e32 v6, 0
